# P10 tail: final_norm loads hoisted before the row reduction, stores back to back
# baseline (speedup 1.0000x reference)
; __device__ __forceinline__ float sigmoid_f(float x) { return __builtin_amdgcn_rcpf(1.0f + __expf(-x)); }
; __device__ __forceinline__ void p7_final(Frame& F) {
;     ...
;         const int b = F.wave; float v[32]; float s = 0.f;
; #pragma unroll
;         for (int j = 0; j < 32; ++j) { const int c = F.lane + 64 * j; const float h = SSP(S_H2)[(size_t)b * D + c] + SSP(S_PP)[(size_t)b * D + c] * sigmoid_f(SSP(S_PG)[(size_t)b * D + c]); v[j] = h; s += h * h; }
.LBB0_2174:
	s_add_u32 s2, s26, 0x30851400
	s_addc_u32 s3, s27, 0
	s_lshl_b64 s[8:9], s[94:95], 11
	s_add_u32 s4, s26, 0x30871400
	s_addc_u32 s5, s27, 0
	s_add_u32 s6, s26, 0x30861400
	s_waitcnt vmcnt(32)
	v_or_b32_e32 v2, s8, v199
	v_mov_b32_e32 v3, s9
	s_addc_u32 s7, s27, 0
	v_lshlrev_b64 v[4:5], 2, v[2:3]
	s_waitcnt vmcnt(1)
	v_lshl_add_u64 v[12:13], s[2:3], 0, v[4:5]
	v_lshl_add_u64 v[14:15], s[4:5], 0, v[4:5]
	s_waitcnt vmcnt(0)
	v_lshl_add_u64 v[6:7], s[6:7], 0, v[4:5]
	v_or_b32_e32 v4, 64, v199
	v_or_b32_e32 v2, s8, v4
	v_lshlrev_b64 v[8:9], 2, v[2:3]
	v_or_b32_e32 v5, 0x80, v199
	v_lshl_add_u64 v[10:11], s[6:7], 0, v[8:9]
	v_or_b32_e32 v2, s8, v5
	global_load_dword v1, v[6:7], off
	global_load_dword v38, v[10:11], off
	v_lshlrev_b64 v[10:11], 2, v[2:3]
	v_lshl_add_u64 v[6:7], s[6:7], 0, v[10:11]
	global_load_dword v39, v[6:7], off
	v_or_b32_e32 v6, 0xc0, v199
	v_or_b32_e32 v2, s8, v6
	v_lshlrev_b64 v[16:17], 2, v[2:3]
	v_lshl_add_u64 v[18:19], s[6:7], 0, v[16:17]
	global_load_dword v40, v[18:19], off
	v_lshl_add_u64 v[18:19], s[2:3], 0, v[8:9]
	v_lshl_add_u64 v[20:21], s[4:5], 0, v[8:9]
	v_lshl_add_u64 v[22:23], s[2:3], 0, v[10:11]
	v_lshl_add_u64 v[24:25], s[4:5], 0, v[10:11]
	global_load_dword v10, v[12:13], off
	global_load_dword v41, v[14:15], off
	global_load_dword v9, v[18:19], off
	global_load_dword v42, v[20:21], off
	global_load_dword v7, v[22:23], off
	global_load_dword v43, v[24:25], off
	v_or_b32_e32 v8, 0x100, v199
	v_or_b32_e32 v11, 0x140, v199
	v_or_b32_e32 v2, s8, v8
	v_lshl_add_u64 v[20:21], s[2:3], 0, v[16:17]
	v_lshl_add_u64 v[22:23], s[4:5], 0, v[16:17]
	v_lshlrev_b64 v[16:17], 2, v[2:3]
	v_or_b32_e32 v2, s8, v11
	v_lshl_add_u64 v[24:25], s[2:3], 0, v[16:17]
	v_lshl_add_u64 v[26:27], s[4:5], 0, v[16:17]
	v_lshl_add_u64 v[28:29], s[6:7], 0, v[16:17]
	v_lshlrev_b64 v[16:17], 2, v[2:3]
	s_load_dwordx2 s[0:1], s[0:1], s10 offset:0x0
	v_lshl_add_u64 v[30:31], s[2:3], 0, v[16:17]
	v_lshl_add_u64 v[32:33], s[4:5], 0, v[16:17]
	v_lshl_add_u64 v[34:35], s[6:7], 0, v[16:17]
	global_load_dword v18, v[20:21], off
	global_load_dword v50, v[22:23], off
	global_load_dword v16, v[24:25], off
	global_load_dword v51, v[26:27], off
	global_load_dword v52, v[28:29], off
	global_load_dword v15, v[30:31], off
	v_or_b32_e32 v12, 0x180, v199
	v_or_b32_e32 v13, 0x1c0, v199
	v_or_b32_e32 v2, s8, v12
	v_lshlrev_b64 v[36:37], 2, v[2:3]
	v_or_b32_e32 v2, s8, v13
	v_lshlrev_b64 v[26:27], 2, v[2:3]
	v_lshl_add_u64 v[20:21], s[2:3], 0, v[36:37]
	v_lshl_add_u64 v[22:23], s[4:5], 0, v[36:37]
	v_lshl_add_u64 v[24:25], s[6:7], 0, v[36:37]
	v_lshl_add_u64 v[28:29], s[2:3], 0, v[26:27]
	v_lshl_add_u64 v[30:31], s[4:5], 0, v[26:27]
	v_lshl_add_u64 v[26:27], s[6:7], 0, v[26:27]
	global_load_dword v53, v[32:33], off
	global_load_dword v36, v[34:35], off
	global_load_dword v19, v[20:21], off
	global_load_dword v54, v[22:23], off
	global_load_dword v55, v[24:25], off
	global_load_dword v17, v[28:29], off
	global_load_dword v56, v[30:31], off
	global_load_dword v57, v[26:27], off
	v_or_b32_e32 v14, 0x200, v199
	v_or_b32_e32 v25, 0x2c0, v199
	v_or_b32_e32 v110, 0x740, v199
	v_or_b32_e32 v112, 0x780, v199
	v_or_b32_e32 v113, 0x7c0, v0
	v_lshlrev_b32_e32 v4, 2, v4
	v_lshlrev_b32_e32 v5, 2, v5
	s_waitcnt vmcnt(23)
	v_mul_f32_e32 v1, 0xbfb8aa3b, v1
	s_waitcnt vmcnt(22)
	v_mul_f32_e32 v2, 0xbfb8aa3b, v38
	v_exp_f32_e32 v2, v2
	v_exp_f32_e32 v1, v1
	s_waitcnt vmcnt(21)
	v_mul_f32_e32 v20, 0xbfb8aa3b, v39
	v_exp_f32_e32 v20, v20
	v_add_f32_e32 v2, 1.0, v2
	v_rcp_f32_e32 v2, v2
	v_add_f32_e32 v1, 1.0, v1
	v_add_f32_e32 v20, 1.0, v20
	v_rcp_f32_e32 v20, v20
	s_waitcnt vmcnt(20)
	v_mul_f32_e32 v21, 0xbfb8aa3b, v40
	s_waitcnt vmcnt(16)
	v_fmac_f32_e32 v9, v42, v2
	v_or_b32_e32 v2, s8, v14
	v_rcp_f32_e32 v1, v1
	v_exp_f32_e32 v58, v21
	s_waitcnt vmcnt(14)
	v_fmac_f32_e32 v7, v43, v20
	v_lshlrev_b64 v[20:21], 2, v[2:3]
	v_lshl_add_u64 v[26:27], s[2:3], 0, v[20:21]
	v_lshl_add_u64 v[28:29], s[4:5], 0, v[20:21]
	v_lshl_add_u64 v[30:31], s[6:7], 0, v[20:21]
	v_or_b32_e32 v20, 0x240, v199
	v_or_b32_e32 v2, s8, v20
	v_or_b32_e32 v21, 0x280, v199
	v_lshlrev_b64 v[22:23], 2, v[2:3]
	v_or_b32_e32 v2, s8, v21
	v_fmac_f32_e32 v10, v41, v1
	v_lshlrev_b64 v[40:41], 2, v[2:3]
	v_lshl_add_u64 v[32:33], s[2:3], 0, v[22:23]
	v_lshl_add_u64 v[34:35], s[4:5], 0, v[22:23]
	v_lshl_add_u64 v[38:39], s[6:7], 0, v[22:23]
	v_lshl_add_u64 v[42:43], s[2:3], 0, v[40:41]
	v_lshl_add_u64 v[44:45], s[4:5], 0, v[40:41]
	global_load_dword v24, v[26:27], off
	global_load_dword v1, v[28:29], off
	global_load_dword v59, v[30:31], off
	global_load_dword v23, v[32:33], off
	global_load_dword v60, v[34:35], off
	global_load_dword v61, v[38:39], off
	global_load_dword v22, v[42:43], off
	global_load_dword v62, v[44:45], off
	v_or_b32_e32 v2, s8, v25
	v_lshlrev_b64 v[26:27], 2, v[2:3]
	v_lshl_add_u64 v[32:33], s[2:3], 0, v[26:27]
	v_lshl_add_u64 v[34:35], s[4:5], 0, v[26:27]
	v_lshl_add_u64 v[38:39], s[6:7], 0, v[26:27]
	v_or_b32_e32 v26, 0x300, v199
	v_or_b32_e32 v2, s8, v26
	v_lshl_add_u64 v[30:31], s[6:7], 0, v[40:41]
	v_lshlrev_b64 v[28:29], 2, v[2:3]
	v_lshl_add_u64 v[40:41], s[2:3], 0, v[28:29]
	v_lshl_add_u64 v[42:43], s[4:5], 0, v[28:29]
	v_lshl_add_u64 v[44:45], s[6:7], 0, v[28:29]
	global_load_dword v63, v[30:31], off
	global_load_dword v28, v[32:33], off
	global_load_dword v64, v[34:35], off
	global_load_dword v65, v[38:39], off
	global_load_dword v27, v[40:41], off
	global_load_dword v66, v[42:43], off
	global_load_dword v67, v[44:45], off
	v_or_b32_e32 v29, 0x340, v199
	v_or_b32_e32 v2, s8, v29
	v_or_b32_e32 v30, 0x380, v199
	v_lshlrev_b64 v[34:35], 2, v[2:3]
	v_or_b32_e32 v2, s8, v30
	v_or_b32_e32 v31, 0x3c0, v0
	v_lshl_add_u64 v[32:33], s[6:7], 0, v[34:35]
	v_lshlrev_b64 v[40:41], 2, v[2:3]
	v_or_b32_e32 v2, s8, v31
	v_lshl_add_u64 v[42:43], s[2:3], 0, v[40:41]
	v_lshl_add_u64 v[44:45], s[4:5], 0, v[40:41]
	v_lshl_add_u64 v[40:41], s[6:7], 0, v[40:41]
	global_load_dword v68, v[32:33], off
	global_load_dword v69, v[40:41], off
	v_lshlrev_b64 v[32:33], 2, v[2:3]
	s_waitcnt vmcnt(26)
; __device__ __forceinline__ float sigmoid_f(float x) { return __builtin_amdgcn_rcpf(1.0f + __expf(-x)); }
; __device__ __forceinline__ void p7_final(Frame& F) {
;     ...
;         const int b = F.wave; float v[32]; float s = 0.f;
; #pragma unroll
;         for (int j = 0; j < 32; ++j) { const int c = F.lane + 64 * j; const float h = SSP(S_H2)[(size_t)b * D + c] + SSP(S_PP)[(size_t)b * D + c] * sigmoid_f(SSP(S_PG)[(size_t)b * D + c]); v[j] = h; s += h * h; }
	v_mul_f32_e32 v2, 0xbfb8aa3b, v52
	v_exp_f32_e32 v2, v2
	v_lshl_add_u64 v[38:39], s[4:5], 0, v[34:35]
	v_lshl_add_u64 v[34:35], s[2:3], 0, v[34:35]
	v_lshl_add_u64 v[40:41], s[2:3], 0, v[32:33]
	v_lshl_add_u64 v[46:47], s[4:5], 0, v[32:33]
	v_lshl_add_u64 v[48:49], s[6:7], 0, v[32:33]
	global_load_dword v70, v[38:39], off
	global_load_dword v33, v[42:43], off
	global_load_dword v71, v[44:45], off
	global_load_dword v32, v[40:41], off
	global_load_dword v72, v[46:47], off
	global_load_dword v73, v[48:49], off
	v_add_f32_e32 v2, 1.0, v2
	global_load_dword v34, v[34:35], off
	v_add_f32_e32 v35, 1.0, v58
	s_waitcnt vmcnt(30)
	v_mul_f32_e32 v36, 0xbfb8aa3b, v36
	v_rcp_f32_e32 v35, v35
	v_rcp_f32_e32 v2, v2
	v_exp_f32_e32 v36, v36
	v_mul_f32_e32 v37, v9, v9
	v_fmac_f32_e32 v18, v50, v35
	v_fmac_f32_e32 v16, v51, v2
	v_add_f32_e32 v2, 1.0, v36
	v_or_b32_e32 v35, 0x400, v199
	v_rcp_f32_e32 v44, v2
	v_or_b32_e32 v2, s8, v35
	v_lshlrev_b64 v[38:39], 2, v[2:3]
	v_lshl_add_u64 v[40:41], s[6:7], 0, v[38:39]
	global_load_dword v58, v[40:41], off
	s_waitcnt vmcnt(28)
	v_mul_f32_e32 v36, 0xbfb8aa3b, v55
	v_exp_f32_e32 v45, v36
	v_or_b32_e32 v36, 0x440, v199
	v_or_b32_e32 v2, s8, v36
	v_lshlrev_b64 v[40:41], 2, v[2:3]
	v_lshl_add_u64 v[42:43], s[6:7], 0, v[40:41]
	global_load_dword v74, v[42:43], off
	v_add_f32_e32 v2, 1.0, v45
	v_rcp_f32_e32 v2, v2
	v_fmac_f32_e32 v15, v53, v44
	v_lshl_add_u64 v[44:45], s[4:5], 0, v[38:39]
	v_lshl_add_u64 v[46:47], s[2:3], 0, v[40:41]
	v_fmac_f32_e32 v19, v54, v2
	s_waitcnt vmcnt(26)
	v_mul_f32_e32 v2, 0xbfb8aa3b, v57
	v_exp_f32_e32 v2, v2
	v_lshl_add_u64 v[48:49], s[4:5], 0, v[40:41]
	v_fmac_f32_e32 v37, v10, v10
	v_fmac_f32_e32 v37, v7, v7
	v_add_f32_e32 v2, 1.0, v2
	v_rcp_f32_e32 v2, v2
	v_fmac_f32_e32 v37, v18, v18
	v_fmac_f32_e32 v37, v16, v16
	s_waitcnt vmcnt(23)
	v_mul_f32_e32 v42, 0xbfb8aa3b, v59
	v_exp_f32_e32 v42, v42
	v_fmac_f32_e32 v17, v56, v2
	s_waitcnt vmcnt(20)
	v_mul_f32_e32 v43, 0xbfb8aa3b, v61
	v_exp_f32_e32 v43, v43
	v_add_f32_e32 v42, 1.0, v42
	v_rcp_f32_e32 v42, v42
	v_fmac_f32_e32 v37, v15, v15
	v_fmac_f32_e32 v37, v19, v19
	v_fmac_f32_e32 v37, v17, v17
	v_fmac_f32_e32 v24, v1, v42
	v_add_f32_e32 v1, 1.0, v43
	s_waitcnt vmcnt(17)
	v_mul_f32_e32 v2, 0xbfb8aa3b, v63
	v_rcp_f32_e32 v1, v1
	v_exp_f32_e32 v2, v2
	v_fmac_f32_e32 v37, v24, v24
	v_fmac_f32_e32 v23, v60, v1
	v_add_f32_e32 v1, 1.0, v2
	s_waitcnt vmcnt(14)
	v_mul_f32_e32 v2, 0xbfb8aa3b, v65
	v_rcp_f32_e32 v1, v1
	v_exp_f32_e32 v2, v2
	s_waitcnt vmcnt(11)
	v_mul_f32_e32 v42, 0xbfb8aa3b, v67
	v_exp_f32_e32 v42, v42
	v_fmac_f32_e32 v22, v62, v1
	v_add_f32_e32 v1, 1.0, v2
	v_rcp_f32_e32 v1, v1
	v_add_f32_e32 v2, 1.0, v42
	v_rcp_f32_e32 v2, v2
	v_fmac_f32_e32 v37, v23, v23
	v_fmac_f32_e32 v28, v64, v1
	s_waitcnt vmcnt(10)
	v_mul_f32_e32 v1, 0xbfb8aa3b, v68
	v_fmac_f32_e32 v27, v66, v2
	v_exp_f32_e32 v1, v1
	s_waitcnt vmcnt(9)
	v_mul_f32_e32 v2, 0xbfb8aa3b, v69
	v_exp_f32_e32 v2, v2
	v_fmac_f32_e32 v37, v22, v22
	v_add_f32_e32 v1, 1.0, v1
	v_rcp_f32_e32 v1, v1
	v_add_f32_e32 v2, 1.0, v2
	s_waitcnt vmcnt(3)
	v_mul_f32_e32 v42, 0xbfb8aa3b, v73
	v_exp_f32_e32 v42, v42
	v_rcp_f32_e32 v2, v2
	s_waitcnt vmcnt(2)
	v_fmac_f32_e32 v34, v70, v1
	v_fmac_f32_e32 v37, v28, v28
	v_add_f32_e32 v1, 1.0, v42
	v_lshl_add_u64 v[42:43], s[2:3], 0, v[38:39]
	v_or_b32_e32 v38, 0x480, v199
	v_fmac_f32_e32 v33, v71, v2
	v_or_b32_e32 v2, s8, v38
	v_lshlrev_b64 v[50:51], 2, v[2:3]
	v_lshl_add_u64 v[52:53], s[2:3], 0, v[50:51]
	v_lshl_add_u64 v[54:55], s[4:5], 0, v[50:51]
	global_load_dword v41, v[42:43], off
	global_load_dword v84, v[44:45], off
	global_load_dword v40, v[46:47], off
	global_load_dword v85, v[48:49], off
	global_load_dword v39, v[52:53], off
	global_load_dword v86, v[54:55], off
	v_or_b32_e32 v42, 0x4c0, v199
	v_or_b32_e32 v43, 0x500, v199
	v_lshl_add_u64 v[48:49], s[6:7], 0, v[50:51]
	s_waitcnt vmcnt(7)
	v_mul_f32_e32 v2, 0xbfb8aa3b, v58
	v_exp_f32_e32 v2, v2
	v_rcp_f32_e32 v1, v1
	v_fmac_f32_e32 v37, v27, v27
	v_fmac_f32_e32 v37, v34, v34
	v_add_f32_e32 v87, 1.0, v2
	v_or_b32_e32 v2, s8, v42
	v_lshlrev_b64 v[44:45], 2, v[2:3]
	v_or_b32_e32 v2, s8, v43
	v_lshl_add_u64 v[50:51], s[2:3], 0, v[44:45]
	v_lshl_add_u64 v[52:53], s[4:5], 0, v[44:45]
	v_lshl_add_u64 v[54:55], s[6:7], 0, v[44:45]
	v_lshlrev_b64 v[44:45], 2, v[2:3]
	v_lshl_add_u64 v[56:57], s[2:3], 0, v[44:45]
	v_lshl_add_u64 v[58:59], s[4:5], 0, v[44:45]
	v_lshl_add_u64 v[60:61], s[6:7], 0, v[44:45]
	v_or_b32_e32 v44, 0x540, v199
	v_or_b32_e32 v2, s8, v44
	v_lshlrev_b64 v[62:63], 2, v[2:3]
	v_lshl_add_u64 v[64:65], s[2:3], 0, v[62:63]
	global_load_dword v89, v[48:49], off
	global_load_dword v47, v[50:51], off
	global_load_dword v90, v[52:53], off
	global_load_dword v91, v[54:55], off
	global_load_dword v46, v[56:57], off
	global_load_dword v92, v[58:59], off
	global_load_dword v93, v[60:61], off
	global_load_dword v45, v[64:65], off
	v_or_b32_e32 v48, 0x580, v199
	v_or_b32_e32 v2, s8, v48
	v_or_b32_e32 v49, 0x5c0, v199
	v_lshlrev_b64 v[50:51], 2, v[2:3]
	v_or_b32_e32 v2, s8, v49
	v_lshl_add_u64 v[52:53], s[4:5], 0, v[62:63]
	v_lshl_add_u64 v[56:57], s[2:3], 0, v[50:51]
	v_lshl_add_u64 v[58:59], s[4:5], 0, v[50:51]
	v_lshl_add_u64 v[60:61], s[6:7], 0, v[50:51]
	v_lshlrev_b64 v[50:51], 2, v[2:3]
	v_lshl_add_u64 v[54:55], s[6:7], 0, v[62:63]
	v_lshl_add_u64 v[62:63], s[2:3], 0, v[50:51]
	v_lshl_add_u64 v[64:65], s[4:5], 0, v[50:51]
	v_lshl_add_u64 v[66:67], s[6:7], 0, v[50:51]
	global_load_dword v94, v[52:53], off
	global_load_dword v95, v[54:55], off
	global_load_dword v51, v[56:57], off
	global_load_dword v96, v[58:59], off
	global_load_dword v97, v[60:61], off
	global_load_dword v50, v[62:63], off
	global_load_dword v98, v[64:65], off
	global_load_dword v99, v[66:67], off
	v_or_b32_e32 v52, 0x600, v199
	v_or_b32_e32 v2, s8, v52
	v_or_b32_e32 v53, 0x640, v199
	v_lshlrev_b64 v[54:55], 2, v[2:3]
	v_or_b32_e32 v2, s8, v53
	v_lshl_add_u64 v[58:59], s[2:3], 0, v[54:55]
	v_lshl_add_u64 v[60:61], s[4:5], 0, v[54:55]
	v_lshl_add_u64 v[62:63], s[6:7], 0, v[54:55]
	v_lshlrev_b64 v[54:55], 2, v[2:3]
	v_lshl_add_u64 v[64:65], s[2:3], 0, v[54:55]
	v_lshl_add_u64 v[66:67], s[4:5], 0, v[54:55]
	v_lshl_add_u64 v[68:69], s[6:7], 0, v[54:55]
	v_or_b32_e32 v54, 0x680, v199
	v_or_b32_e32 v2, s8, v54
	v_lshlrev_b64 v[70:71], 2, v[2:3]
	v_fmac_f32_e32 v32, v72, v1
	s_waitcnt vmcnt(22)
; __device__ __forceinline__ float sigmoid_f(float x) { return __builtin_amdgcn_rcpf(1.0f + __expf(-x)); }
; __device__ __forceinline__ void p7_final(Frame& F) {
;     ...
;         const int b = F.wave; float v[32]; float s = 0.f;
; #pragma unroll
;         for (int j = 0; j < 32; ++j) { const int c = F.lane + 64 * j; const float h = SSP(S_H2)[(size_t)b * D + c] + SSP(S_PP)[(size_t)b * D + c] * sigmoid_f(SSP(S_PG)[(size_t)b * D + c]); v[j] = h; s += h * h; }
;         const float rs = rsqrtf(wave_sum(s) * (1.f / D) + EPS);
	v_mul_f32_e32 v1, 0xbfb8aa3b, v74
	v_lshl_add_u64 v[72:73], s[2:3], 0, v[70:71]
	v_lshl_add_u64 v[74:75], s[4:5], 0, v[70:71]
	global_load_dword v57, v[58:59], off
	global_load_dword v100, v[60:61], off
	global_load_dword v101, v[62:63], off
	global_load_dword v56, v[64:65], off
	global_load_dword v102, v[66:67], off
	global_load_dword v103, v[68:69], off
	global_load_dword v55, v[72:73], off
	global_load_dword v104, v[74:75], off
	v_or_b32_e32 v58, 0x6c0, v199
	v_or_b32_e32 v2, s8, v58
	v_or_b32_e32 v59, 0x700, v199
	v_lshlrev_b64 v[62:63], 2, v[2:3]
	v_or_b32_e32 v2, s8, v59
	v_lshl_add_u64 v[60:61], s[6:7], 0, v[70:71]
	v_lshlrev_b64 v[68:69], 2, v[2:3]
	v_lshl_add_u64 v[64:65], s[2:3], 0, v[62:63]
	v_lshl_add_u64 v[66:67], s[4:5], 0, v[62:63]
	v_lshl_add_u64 v[62:63], s[6:7], 0, v[62:63]
	v_lshl_add_u64 v[70:71], s[2:3], 0, v[68:69]
	v_lshl_add_u64 v[72:73], s[4:5], 0, v[68:69]
	v_lshl_add_u64 v[68:69], s[6:7], 0, v[68:69]
	global_load_dword v105, v[60:61], off
	global_load_dword v106, v[64:65], off
	global_load_dword v107, v[66:67], off
	global_load_dword v108, v[62:63], off
	global_load_dword v109, v[68:69], off
	v_or_b32_e32 v2, s8, v110
	v_lshlrev_b64 v[60:61], 2, v[2:3]
	v_lshl_add_u64 v[62:63], s[2:3], 0, v[60:61]
	v_lshl_add_u64 v[64:65], s[4:5], 0, v[60:61]
	v_lshl_add_u64 v[60:61], s[6:7], 0, v[60:61]
	global_load_dword v111, v[60:61], off
	v_or_b32_e32 v2, s8, v112
	v_lshlrev_b64 v[60:61], 2, v[2:3]
	v_or_b32_e32 v2, s8, v113
	v_exp_f32_e32 v88, v1
	v_lshlrev_b64 v[0:1], 2, v[2:3]
	v_lshl_add_u64 v[66:67], s[2:3], 0, v[60:61]
	v_lshl_add_u64 v[68:69], s[4:5], 0, v[60:61]
	v_lshl_add_u64 v[60:61], s[6:7], 0, v[60:61]
	v_lshl_add_u64 v[2:3], s[2:3], 0, v[0:1]
	v_lshl_add_u64 v[74:75], s[4:5], 0, v[0:1]
	v_lshl_add_u64 v[0:1], s[6:7], 0, v[0:1]
	global_load_dword v77, v[64:65], off
	global_load_dword v78, v[66:67], off
	global_load_dword v80, v[68:69], off
	global_load_dword v114, v[60:61], off
	global_load_dword v79, v[2:3], off
	global_load_dword v81, v[74:75], off
	global_load_dword v115, v[0:1], off
	global_load_dword v82, v[70:71], off
	global_load_dword v76, v[72:73], off
	global_load_dword v83, v[62:63], off
	v_add_f32_e32 v1, 1.0, v88
	v_rcp_f32_e32 v0, v87
	v_rcp_f32_e32 v1, v1
	v_fmac_f32_e32 v37, v33, v33
	v_fmac_f32_e32 v37, v32, v32
	s_waitcnt vmcnt(39)
	v_mul_f32_e32 v2, 0xbfb8aa3b, v89
	v_exp_f32_e32 v2, v2
	v_fmac_f32_e32 v41, v84, v0
	v_fmac_f32_e32 v40, v85, v1
	s_waitcnt vmcnt(36)
	v_mul_f32_e32 v1, 0xbfb8aa3b, v91
	v_add_f32_e32 v0, 1.0, v2
	v_rcp_f32_e32 v0, v0
	v_exp_f32_e32 v1, v1
	v_fmac_f32_e32 v37, v41, v41
	v_fmac_f32_e32 v37, v40, v40
	v_fmac_f32_e32 v39, v86, v0
	v_add_f32_e32 v0, 1.0, v1
	s_waitcnt vmcnt(33)
	v_mul_f32_e32 v1, 0xbfb8aa3b, v93
	v_rcp_f32_e32 v0, v0
	v_exp_f32_e32 v1, v1
	v_lshlrev_b32_e32 v62, 2, v199
	s_waitcnt vmcnt(30)
	v_mul_f32_e32 v2, 0xbfb8aa3b, v95
	v_exp_f32_e32 v2, v2
	v_fmac_f32_e32 v47, v90, v0
	v_add_f32_e32 v0, 1.0, v1
	v_rcp_f32_e32 v0, v0
	v_add_f32_e32 v1, 1.0, v2
	v_rcp_f32_e32 v1, v1
	v_fmac_f32_e32 v37, v39, v39
	v_fmac_f32_e32 v46, v92, v0
	s_waitcnt vmcnt(27)
	v_mul_f32_e32 v0, 0xbfb8aa3b, v97
	v_fmac_f32_e32 v45, v94, v1
	s_waitcnt vmcnt(24)
	v_mul_f32_e32 v1, 0xbfb8aa3b, v99
	v_exp_f32_e32 v0, v0
	v_exp_f32_e32 v1, v1
	s_waitcnt lgkmcnt(0)
	global_load_dword v63, v62, s[0:1]
	v_fmac_f32_e32 v37, v47, v47
	v_add_f32_e32 v0, 1.0, v0
	v_add_f32_e32 v1, 1.0, v1
	v_rcp_f32_e32 v0, v0
	v_rcp_f32_e32 v1, v1
	v_fmac_f32_e32 v37, v46, v46
	s_waitcnt vmcnt(22)
	v_mul_f32_e32 v2, 0xbfb8aa3b, v101
	v_exp_f32_e32 v2, v2
	v_fmac_f32_e32 v51, v96, v0
	v_fmac_f32_e32 v50, v98, v1
	s_waitcnt vmcnt(19)
	v_mul_f32_e32 v1, 0xbfb8aa3b, v103
	v_add_f32_e32 v0, 1.0, v2
	v_rcp_f32_e32 v0, v0
	v_exp_f32_e32 v1, v1
	v_fmac_f32_e32 v37, v45, v45
	v_fmac_f32_e32 v37, v51, v51
	v_fmac_f32_e32 v57, v100, v0
	v_add_f32_e32 v0, 1.0, v1
	v_rcp_f32_e32 v0, v0
	v_fmac_f32_e32 v37, v50, v50
	v_fmac_f32_e32 v37, v57, v57
	s_waitcnt vmcnt(16)
	v_mul_f32_e32 v1, 0xbfb8aa3b, v105
	v_exp_f32_e32 v1, v1
	v_fmac_f32_e32 v56, v102, v0
	s_waitcnt vmcnt(13)
	v_mul_f32_e32 v2, 0xbfb8aa3b, v108
	v_exp_f32_e32 v2, v2
	v_add_f32_e32 v0, 1.0, v1
	v_rcp_f32_e32 v0, v0
	v_fmac_f32_e32 v37, v56, v56
	v_add_f32_e32 v1, 1.0, v2
	v_rcp_f32_e32 v1, v1
	v_fmac_f32_e32 v55, v104, v0
	s_waitcnt vmcnt(12)
	v_mul_f32_e32 v0, 0xbfb8aa3b, v109
	v_exp_f32_e32 v0, v0
	v_fmac_f32_e32 v106, v107, v1
	s_waitcnt vmcnt(11)
	v_mul_f32_e32 v1, 0xbfb8aa3b, v111
	v_exp_f32_e32 v1, v1
	s_waitcnt vmcnt(7)
	v_mul_f32_e32 v2, 0xbfb8aa3b, v114
	v_exp_f32_e32 v2, v2
	v_add_f32_e32 v0, 1.0, v0
	s_waitcnt vmcnt(4)
	v_mul_f32_e32 v3, 0xbfb8aa3b, v115
	v_exp_f32_e32 v3, v3
	v_add_f32_e32 v1, 1.0, v1
	v_rcp_f32_e32 v0, v0
	v_rcp_f32_e32 v1, v1
	v_add_f32_e32 v2, 1.0, v2
	v_add_f32_e32 v3, 1.0, v3
	v_rcp_f32_e32 v2, v2
	v_rcp_f32_e32 v3, v3
	v_fmac_f32_e32 v37, v55, v55
	s_waitcnt vmcnt(1)
; __device__ __forceinline__ float sigmoid_f(float x) { return __builtin_amdgcn_rcpf(1.0f + __expf(-x)); }
; __device__ __forceinline__ float wave_sum(float v) {
; #pragma unroll
;     for (int o = 1; o < 64; o <<= 1) v += __shfl_xor(v, o);
;     return v;
; __device__ __forceinline__ void p7_final(Frame& F) {
;     ...
;         for (int j = 0; j < 32; ++j) { const int c = F.lane + 64 * j; const float h = SSP(S_H2)[(size_t)b * D + c] + SSP(S_PP)[(size_t)b * D + c] * sigmoid_f(SSP(S_PG)[(size_t)b * D + c]); v[j] = h; s += h * h; }
;         const float rs = rsqrtf(wave_sum(s) * (1.f / D) + EPS);
; #pragma unroll
;         for (int j = 0; j < 32; ++j) { const int c = F.lane + 64 * j; F.out[OUT_YS + (size_t)b * D + c] = v[j] * rs * fw[c]; }
	v_pk_fma_f32 v[0:1], v[76:77], v[0:1], v[82:83]
	v_fmac_f32_e32 v37, v106, v106
	v_pk_mul_f32 v[60:61], v[0:1], v[0:1]
	v_pk_fma_f32 v[2:3], v[80:81], v[2:3], v[78:79]
	v_add_f32_e32 v37, v37, v60
	v_add_f32_e32 v37, v37, v61
	v_pk_mul_f32 v[60:61], v[2:3], v[2:3]
	s_mov_b32 s2, 0x800000
	v_add_f32_e32 v37, v37, v60
	v_add_u32_e32 v120, 0x1000, v62
	global_load_dword v121, v62, s[0:1] offset:256
	global_load_dword v122, v62, s[0:1] offset:512
	global_load_dword v123, v62, s[0:1] offset:768
	global_load_dword v124, v62, s[0:1] offset:1024
	global_load_dword v125, v62, s[0:1] offset:1280
	global_load_dword v126, v62, s[0:1] offset:1536
	global_load_dword v127, v62, s[0:1] offset:1792
	global_load_dword v128, v62, s[0:1] offset:2048
	global_load_dword v129, v62, s[0:1] offset:2304
	global_load_dword v130, v62, s[0:1] offset:2560
	global_load_dword v131, v62, s[0:1] offset:2816
	global_load_dword v132, v62, s[0:1] offset:3072
	global_load_dword v133, v62, s[0:1] offset:3328
	global_load_dword v134, v62, s[0:1] offset:3584
	global_load_dword v135, v62, s[0:1] offset:3840
	global_load_dword v136, v120, s[0:1] offset:0
	global_load_dword v137, v120, s[0:1] offset:256
	global_load_dword v138, v120, s[0:1] offset:512
	global_load_dword v139, v120, s[0:1] offset:768
	global_load_dword v140, v120, s[0:1] offset:1024
	global_load_dword v141, v120, s[0:1] offset:1280
	global_load_dword v142, v120, s[0:1] offset:1536
	global_load_dword v143, v120, s[0:1] offset:1792
	global_load_dword v144, v120, s[0:1] offset:2048
	global_load_dword v145, v120, s[0:1] offset:2304
	global_load_dword v146, v120, s[0:1] offset:2560
	global_load_dword v147, v120, s[0:1] offset:2816
	global_load_dword v148, v120, s[0:1] offset:3072
	global_load_dword v149, v120, s[0:1] offset:3328
	global_load_dword v150, v120, s[0:1] offset:3584
	global_load_dword v151, v120, s[0:1] offset:3840
	v_mbcnt_lo_u32_b32 v60, -1, 0
	v_mbcnt_hi_u32_b32 v60, -1, v60
	v_add_f32_e32 v37, v37, v61
	v_and_b32_e32 v61, 64, v60
	v_add_u32_e32 v61, 64, v61
	v_xor_b32_e32 v64, 1, v60
	v_cmp_lt_i32_e32 vcc, v64, v61
	s_nop 1
	v_cndmask_b32_e32 v64, v60, v64, vcc
	v_lshlrev_b32_e32 v64, 2, v64
	ds_bpermute_b32 v64, v64, v37
	s_waitcnt lgkmcnt(0)
	v_add_f32_e32 v37, v37, v64
	v_xor_b32_e32 v64, 2, v60
	v_cmp_lt_i32_e32 vcc, v64, v61
	s_nop 1
	v_cndmask_b32_e32 v64, v60, v64, vcc
	v_lshlrev_b32_e32 v64, 2, v64
	ds_bpermute_b32 v64, v64, v37
	s_waitcnt lgkmcnt(0)
	v_add_f32_e32 v37, v37, v64
	v_xor_b32_e32 v64, 4, v60
	v_cmp_lt_i32_e32 vcc, v64, v61
	s_nop 1
	v_cndmask_b32_e32 v64, v60, v64, vcc
	v_lshlrev_b32_e32 v64, 2, v64
	ds_bpermute_b32 v64, v64, v37
	s_waitcnt lgkmcnt(0)
	v_add_f32_e32 v37, v37, v64
	v_xor_b32_e32 v64, 8, v60
	v_cmp_lt_i32_e32 vcc, v64, v61
	s_nop 1
	v_cndmask_b32_e32 v64, v60, v64, vcc
	v_lshlrev_b32_e32 v64, 2, v64
	ds_bpermute_b32 v64, v64, v37
	s_waitcnt lgkmcnt(0)
	v_add_f32_e32 v37, v37, v64
	v_xor_b32_e32 v64, 16, v60
	v_cmp_lt_i32_e32 vcc, v64, v61
	s_nop 1
	v_cndmask_b32_e32 v64, v60, v64, vcc
	v_lshlrev_b32_e32 v64, 2, v64
	ds_bpermute_b32 v64, v64, v37
	s_waitcnt lgkmcnt(0)
	v_add_f32_e32 v37, v37, v64
	v_xor_b32_e32 v64, 32, v60
	v_cmp_lt_i32_e32 vcc, v64, v61
	s_nop 1
	v_cndmask_b32_e32 v60, v60, v64, vcc
	v_lshlrev_b32_e32 v60, 2, v60
	ds_bpermute_b32 v60, v60, v37
	s_waitcnt lgkmcnt(0)
	v_add_f32_e32 v37, v37, v60
	v_mov_b32_e32 v60, 0x358637bd
	v_fmac_f32_e32 v60, 0x3a000000, v37
	v_mul_f32_e32 v37, 0x4b800000, v60
	v_cmp_gt_f32_e32 vcc, s2, v60
	s_lshl_b64 s[2:3], s[94:95], 13
	s_add_u32 s2, s24, s2
	v_cndmask_b32_e32 v37, v60, v37, vcc
	v_rsq_f32_e32 v37, v37
	s_addc_u32 s3, s25, s3
	s_add_u32 s2, s2, 0x4000000
	s_addc_u32 s3, s3, 0
	v_mul_f32_e32 v60, 0x45800000, v37
	v_cndmask_b32_e32 v37, v37, v60, vcc
	v_mul_f32_e32 v10, v10, v37
	s_waitcnt vmcnt(0)
; __device__ __forceinline__ void p7_final(Frame& F) {
;     ...
;         const float rs = rsqrtf(wave_sum(s) * (1.f / D) + EPS);
; #pragma unroll
;         for (int j = 0; j < 32; ++j) { const int c = F.lane + 64 * j; F.out[OUT_YS + (size_t)b * D + c] = v[j] * rs * fw[c]; }
	v_mul_f32_e32 v10, v63, v10
	global_store_dword v62, v10, s[2:3]
	v_mov_b32_e32 v10, v121
	v_mul_f32_e32 v9, v9, v37
	v_mul_f32_e32 v7, v7, v37
	v_mul_f32_e32 v0, v0, v37
	v_mul_f32_e32 v1, v1, v37
	v_mul_f32_e32 v9, v10, v9
	global_store_dword v4, v9, s[2:3]
	v_mov_b32_e32 v4, v122
	v_mul_f32_e32 v4, v4, v7
	global_store_dword v5, v4, s[2:3]
	v_mov_b32_e32 v4, v123
	v_mul_f32_e32 v5, v18, v37
	v_mul_f32_e32 v7, v33, v37
	v_mul_f32_e32 v4, v4, v5
	v_lshlrev_b32_e32 v5, 2, v6
	global_store_dword v5, v4, s[2:3]
	v_mov_b32_e32 v4, v124
	v_mul_f32_e32 v5, v16, v37
	v_mul_f32_e32 v6, v15, v37
	v_mul_f32_e32 v4, v4, v5
	v_lshlrev_b32_e32 v5, 2, v8
	global_store_dword v5, v4, s[2:3]
	v_mov_b32_e32 v4, v125
	v_lshlrev_b32_e32 v5, 2, v11
	v_mul_f32_e32 v4, v4, v6
	global_store_dword v5, v4, s[2:3]
	v_mov_b32_e32 v4, v126
	v_mul_f32_e32 v6, v19, v37
	v_lshlrev_b32_e32 v5, 2, v12
	v_mul_f32_e32 v4, v4, v6
	global_store_dword v5, v4, s[2:3]
	v_mov_b32_e32 v4, v127
	v_mul_f32_e32 v6, v17, v37
	v_lshlrev_b32_e32 v5, 2, v13
	v_mul_f32_e32 v4, v6, v4
	global_store_dword v5, v4, s[2:3]
	v_mov_b32_e32 v4, v128
	v_mul_f32_e32 v6, v24, v37
	v_lshlrev_b32_e32 v5, 2, v14
	v_mul_f32_e32 v4, v6, v4
	global_store_dword v5, v4, s[2:3]
	v_mov_b32_e32 v4, v129
	v_mul_f32_e32 v6, v23, v37
	v_lshlrev_b32_e32 v5, 2, v20
	v_mul_f32_e32 v4, v6, v4
	global_store_dword v5, v4, s[2:3]
	v_mov_b32_e32 v4, v130
	v_mul_f32_e32 v6, v22, v37
	v_lshlrev_b32_e32 v5, 2, v21
	v_mul_f32_e32 v4, v6, v4
	global_store_dword v5, v4, s[2:3]
	v_mov_b32_e32 v4, v131
	v_mul_f32_e32 v6, v28, v37
	v_lshlrev_b32_e32 v5, 2, v25
	v_mul_f32_e32 v4, v6, v4
	global_store_dword v5, v4, s[2:3]
	v_mov_b32_e32 v4, v132
	v_mul_f32_e32 v6, v27, v37
	v_lshlrev_b32_e32 v5, 2, v26
	v_mul_f32_e32 v4, v6, v4
	global_store_dword v5, v4, s[2:3]
	v_mov_b32_e32 v4, v133
	v_mul_f32_e32 v6, v34, v37
	v_lshlrev_b32_e32 v5, 2, v29
	v_mul_f32_e32 v4, v6, v4
	global_store_dword v5, v4, s[2:3]
	v_mov_b32_e32 v4, v134
	v_lshlrev_b32_e32 v5, 2, v30
	v_lshlrev_b32_e32 v6, 2, v31
	v_mul_f32_e32 v4, v7, v4
	global_store_dword v5, v4, s[2:3]
	v_mov_b32_e32 v4, v135
	v_mul_f32_e32 v7, v32, v37
	v_lshlrev_b32_e32 v5, 2, v35
	v_mul_f32_e32 v4, v7, v4
	global_store_dword v6, v4, s[2:3]
	v_mov_b32_e32 v4, v136
	v_mul_f32_e32 v7, v41, v37
	v_lshlrev_b32_e32 v6, 2, v36
	v_mul_f32_e32 v4, v7, v4
	global_store_dword v5, v4, s[2:3]
	v_mov_b32_e32 v4, v137
	v_mul_f32_e32 v7, v40, v37
	v_lshlrev_b32_e32 v5, 2, v38
	v_mul_f32_e32 v4, v7, v4
	global_store_dword v6, v4, s[2:3]
	v_mov_b32_e32 v4, v138
	v_mul_f32_e32 v7, v39, v37
	v_lshlrev_b32_e32 v6, 2, v42
	v_mul_f32_e32 v4, v7, v4
	global_store_dword v5, v4, s[2:3]
	v_mov_b32_e32 v4, v139
	v_mul_f32_e32 v7, v47, v37
	v_lshlrev_b32_e32 v5, 2, v43
	v_mul_f32_e32 v4, v7, v4
	global_store_dword v6, v4, s[2:3]
	v_mov_b32_e32 v4, v140
	v_mul_f32_e32 v7, v46, v37
	v_lshlrev_b32_e32 v6, 2, v44
	v_mul_f32_e32 v4, v7, v4
	global_store_dword v5, v4, s[2:3]
	v_mov_b32_e32 v4, v141
	v_mul_f32_e32 v7, v45, v37
	v_lshlrev_b32_e32 v5, 2, v48
	v_mul_f32_e32 v4, v7, v4
	global_store_dword v6, v4, s[2:3]
	v_mov_b32_e32 v4, v142
	v_mul_f32_e32 v7, v51, v37
	v_lshlrev_b32_e32 v6, 2, v49
	v_mul_f32_e32 v4, v7, v4
	global_store_dword v5, v4, s[2:3]
	v_mov_b32_e32 v4, v143
	v_mul_f32_e32 v7, v50, v37
	v_lshlrev_b32_e32 v5, 2, v52
	v_mul_f32_e32 v4, v7, v4
	global_store_dword v6, v4, s[2:3]
	v_mov_b32_e32 v4, v144
	v_mul_f32_e32 v7, v57, v37
	v_lshlrev_b32_e32 v6, 2, v53
	v_mul_f32_e32 v4, v7, v4
	global_store_dword v5, v4, s[2:3]
	v_mov_b32_e32 v4, v145
	v_mul_f32_e32 v7, v56, v37
	v_lshlrev_b32_e32 v5, 2, v54
	v_mul_f32_e32 v4, v7, v4
	global_store_dword v6, v4, s[2:3]
	v_mov_b32_e32 v4, v146
	v_mul_f32_e32 v7, v55, v37
	v_lshlrev_b32_e32 v6, 2, v58
	v_mul_f32_e32 v4, v7, v4
	global_store_dword v5, v4, s[2:3]
	v_mov_b32_e32 v4, v147
	v_mul_f32_e32 v7, v106, v37
	v_lshlrev_b32_e32 v5, 2, v59
	v_mul_f32_e32 v4, v7, v4
	global_store_dword v6, v4, s[2:3]
	v_mov_b32_e32 v4, v148
	v_lshlrev_b32_e32 v6, 2, v110
	v_mul_f32_e32 v0, v0, v4
	global_store_dword v5, v0, s[2:3]
	v_mov_b32_e32 v0, v149
	v_lshlrev_b32_e32 v4, 2, v112
	v_mul_f32_e32 v0, v1, v0
	global_store_dword v6, v0, s[2:3]
	v_mov_b32_e32 v0, v150
	v_mul_f32_e32 v1, v2, v37
	v_mul_f32_e32 v2, v3, v37
	v_mul_f32_e32 v0, v1, v0
	global_store_dword v4, v0, s[2:3]
	v_lshlrev_b32_e32 v0, 2, v113
	v_mov_b32_e32 v1, v151
	v_mul_f32_e32 v1, v2, v1
	global_store_dword v0, v1, s[2:3]
	s_endpgm
